# LN0 loop head: first-row loads issued together (one wait instead of three serialized round trips)
# speedup vs baseline: 1.0017x; 1.0017x over previous
.LBB0_133:
	v_add_co_u32_e32 v2, vcc, 0xffff8400, v138
	s_nop 1
	v_addc_co_u32_e32 v3, vcc, -1, v139, vcc
	v_add_co_u32_e32 v4, vcc, 0xffff8800, v138
	s_nop 1
	v_addc_co_u32_e32 v5, vcc, -1, v139, vcc
	global_load_dwordx4 v[18:21], v[2:3], off nt
	global_load_dwordx4 v[10:13], v[4:5], off nt
	v_add_co_u32_e32 v2, vcc, 0xffff8c00, v138
	s_nop 1
	v_addc_co_u32_e32 v3, vcc, -1, v139, vcc
	global_load_dwordx4 v[6:9], v[2:3], off nt
	v_add_co_u32_e32 v2, vcc, 0xffff9000, v138
	s_nop 1
	v_addc_co_u32_e32 v3, vcc, -1, v139, vcc
	global_load_dwordx4 v[2:5], v[2:3], off nt
	v_add_co_u32_e32 v26, vcc, 0xffff9400, v138
	s_nop 1
	v_addc_co_u32_e32 v27, vcc, -1, v139, vcc
	v_add_co_u32_e32 v30, vcc, 0xffff9800, v138
	s_nop 1
	v_addc_co_u32_e32 v31, vcc, -1, v139, vcc
	global_load_dwordx4 v[22:25], v[26:27], off nt
	global_load_dwordx4 v[14:17], v[30:31], off nt
	s_waitcnt vmcnt(3) lgkmcnt(0)
	v_add_f32_e32 v33, v12, v13
	v_add_f32_e32 v35, v8, v9
	v_add_f32_e32 v27, v18, v19
	v_add_f32_e32 v31, v20, v21
	v_add_f32_e32 v27, v27, v31
	v_add_f32_e32 v31, v10, v11
	v_add_f32_e32 v27, 0, v27
	v_add_f32_e32 v31, v31, v33
	v_add_f32_e32 v33, v6, v7
	v_add_f32_e32 v27, v27, v31
	v_add_f32_e32 v31, v33, v35
	v_add_f32_e32 v27, v27, v31
	v_add_co_u32_e32 v28, vcc, 0xffff9c00, v138
	s_waitcnt vmcnt(0) lgkmcnt(0)
	v_add_f32_e32 v33, v2, v3
	v_add_f32_e32 v35, v4, v5
	v_add_f32_e32 v31, v33, v35
	v_add_f32_e32 v27, v27, v31
	ds_swizzle_b32 v31, v27 offset:swizzle(SWAP,1)
	v_addc_co_u32_e32 v29, vcc, -1, v139, vcc
	v_add_co_u32_e32 v26, vcc, 0xffffa000, v138
	s_waitcnt lgkmcnt(0)
	v_add_f32_e32 v27, v27, v31
	ds_swizzle_b32 v31, v27 offset:swizzle(SWAP,2)
	s_mov_b64 s[8:9], vcc
	v_add_co_u32_e32 v32, vcc, 0xffffa400, v138
	s_mov_b64 s[6:7], vcc
	s_waitcnt lgkmcnt(0)
	v_add_f32_e32 v27, v27, v31
	ds_swizzle_b32 v31, v27 offset:swizzle(SWAP,4)
	v_add_co_u32_e32 v34, vcc, 0xffffa800, v138
	s_mov_b64 s[4:5], vcc
	v_add_co_u32_e32 v30, vcc, 0xffffac00, v138
	s_waitcnt lgkmcnt(0)
	v_add_f32_e32 v27, v27, v31
	ds_swizzle_b32 v31, v27 offset:swizzle(SWAP,8)
	s_mov_b64 s[2:3], vcc
	v_add_co_u32_e32 v62, vcc, 0xffffb000, v138
	s_mov_b64 s[28:29], vcc
	s_waitcnt lgkmcnt(0)
	v_add_f32_e32 v27, v27, v31
	ds_swizzle_b32 v31, v27 offset:swizzle(SWAP,16)
	v_add_co_u32_e32 v54, vcc, 0xffffb400, v138
	s_mov_b64 s[24:25], vcc
	v_add_co_u32_e32 v56, vcc, 0xffffb800, v138
	s_waitcnt lgkmcnt(0)
	v_add_f32_e32 v27, v27, v31
	v_mov_b32_e32 v31, v27
	s_nop 1
	v_permlane32_swap_b32_e32 v27, v31
	v_add_f32_e32 v150, v27, v31
	v_fmamk_f32 v21, v150, 0xba800000, v21
	v_fmamk_f32 v19, v150, 0xba800000, v19
	v_fmamk_f32 v20, v150, 0xba800000, v20
	v_fmac_f32_e32 v18, 0xba800000, v150
	v_mul_f32_e32 v27, v19, v19
	v_mul_f32_e32 v31, v21, v21
	v_fmamk_f32 v13, v150, 0xba800000, v13
	v_fmamk_f32 v11, v150, 0xba800000, v11
	v_fmac_f32_e32 v27, v18, v18
	v_fmac_f32_e32 v31, v20, v20
	v_fmamk_f32 v12, v150, 0xba800000, v12
	v_fmac_f32_e32 v10, 0xba800000, v150
	v_add_f32_e32 v27, v27, v31
	v_mul_f32_e32 v31, v11, v11
	v_mul_f32_e32 v33, v13, v13
	v_fmac_f32_e32 v31, v10, v10
	v_fmac_f32_e32 v33, v12, v12
	v_add_f32_e32 v31, v31, v33
	v_fmamk_f32 v9, v150, 0xba800000, v9
	v_fmamk_f32 v7, v150, 0xba800000, v7
	v_add_f32_e32 v27, v27, v31
	v_fmamk_f32 v8, v150, 0xba800000, v8
	v_fmac_f32_e32 v6, 0xba800000, v150
	v_mul_f32_e32 v31, v7, v7
	v_mul_f32_e32 v33, v9, v9
	v_fmac_f32_e32 v31, v6, v6
	v_fmac_f32_e32 v33, v8, v8
	v_add_f32_e32 v31, v31, v33
	v_fmamk_f32 v5, v150, 0xba800000, v5
	v_fmamk_f32 v3, v150, 0xba800000, v3
	v_add_f32_e32 v27, v31, v27
	v_fmamk_f32 v4, v150, 0xba800000, v4
	v_fmac_f32_e32 v2, 0xba800000, v150
	v_mul_f32_e32 v31, v3, v3
	v_mul_f32_e32 v33, v5, v5
	v_fmac_f32_e32 v31, v2, v2
	v_fmac_f32_e32 v33, v4, v4
	v_add_f32_e32 v31, v31, v33
	v_add_f32_e32 v27, v31, v27
	ds_swizzle_b32 v31, v27 offset:swizzle(SWAP,1)
	s_mov_b64 s[26:27], vcc
	v_add_co_u32_e32 v36, vcc, 0xffffbc00, v138
	s_mov_b64 s[18:19], vcc
	s_waitcnt lgkmcnt(0)
	v_add_f32_e32 v27, v27, v31
	ds_swizzle_b32 v31, v27 offset:swizzle(SWAP,2)
	v_add_co_u32_e32 v52, vcc, 0xffffc000, v138
	s_mov_b64 s[22:23], vcc
	v_add_co_u32_e32 v40, vcc, 0xffffc400, v138
	s_waitcnt lgkmcnt(0)
	v_add_f32_e32 v27, v27, v31
	ds_swizzle_b32 v31, v27 offset:swizzle(SWAP,4)
	s_mov_b64 s[16:17], vcc
	v_add_co_u32_e32 v50, vcc, 0xffffc800, v138
	s_mov_b64 s[20:21], vcc
	s_waitcnt lgkmcnt(0)
	v_add_f32_e32 v27, v27, v31
	ds_swizzle_b32 v31, v27 offset:swizzle(SWAP,8)
	v_add_co_u32_e32 v38, vcc, 0xffffcc00, v138
	s_mov_b64 s[12:13], vcc
	v_add_co_u32_e32 v44, vcc, 0xffffd000, v138
	s_mov_b64 s[14:15], vcc
	v_add_co_u32_e32 v42, vcc, 0xffffd400, v138
	s_waitcnt lgkmcnt(0)
	v_add_f32_e32 v31, v27, v31
	s_mov_b64 s[10:11], vcc
	v_add_co_u32_e32 v76, vcc, 0xffffd800, v138
	ds_swizzle_b32 v33, v31 offset:swizzle(SWAP,16)
	s_mov_b64 s[42:43], vcc
	v_add_co_u32_e32 v74, vcc, 0xffffdc00, v138
	s_mov_b64 s[36:37], vcc
	v_add_co_u32_e32 v84, vcc, 0xffffe000, v138
	s_mov_b64 s[40:41], vcc
	v_add_co_u32_e32 v80, vcc, 0xffffe400, v138
	s_mov_b64 s[34:35], vcc
	v_add_co_u32_e32 v82, vcc, 0xffffe800, v138
	global_load_dwordx4 v[46:49], v[28:29], off nt
	s_mov_b64 s[38:39], vcc
	v_add_co_u32_e32 v78, vcc, 0xffffec00, v138
	s_waitcnt lgkmcnt(0)
	v_add_f32_e32 v31, v31, v33
	s_mov_b64 s[30:31], vcc
	v_add_co_u32_e32 v102, vcc, 0xfffff000, v138
	v_mov_b32_e32 v33, v31
	s_mov_b64 s[48:49], vcc
	v_add_co_u32_e32 v104, vcc, 0xfffff400, v138
	v_permlane32_swap_b32_e32 v31, v33
	s_mov_b64 s[44:45], vcc
	v_add_co_u32_e32 v140, vcc, 0xfffff800, v138
	v_add_f32_e32 v31, v31, v33
	s_mov_b64 s[46:47], vcc
	v_addc_co_u32_e64 v27, vcc, -1, v139, s[8:9]
	v_fmamk_f32 v31, v31, 0x3a800000, v1
	v_add_f32_e32 v35, v22, v23
	v_add_f32_e32 v37, v24, v25
	v_mul_f32_e32 v33, 0x4f800000, v31
	v_cmp_gt_f32_e32 vcc, s57, v31
	v_add_f32_e32 v41, v14, v15
	s_nop 0
	v_cndmask_b32_e32 v31, v31, v33, vcc
	v_add_f32_e32 v33, v35, v37
	v_add_f32_e32 v37, 0, v33
	v_addc_co_u32_e64 v33, s[6:7], -1, v139, s[6:7]
	global_load_dwordx4 v[106:109], v[32:33], off nt
	v_sqrt_f32_e32 v39, v31
	global_load_dwordx4 v[26:29], v[26:27], off nt
	v_addc_co_u32_e64 v35, s[4:5], -1, v139, s[4:5]
	v_add_u32_e32 v32, -1, v39
	v_fma_f32 v33, -v32, v39, v31
	v_cmp_ge_f32_e64 s[6:7], 0, v33
	v_add_u32_e32 v33, 1, v39
	global_load_dwordx4 v[70:73], v[34:35], off nt
	v_cndmask_b32_e64 v32, v39, v32, s[6:7]
	v_fma_f32 v39, -v33, v39, v31
	v_cmp_lt_f32_e64 s[4:5], 0, v39
	s_nop 1
	v_cndmask_b32_e64 v32, v32, v33, s[4:5]
	v_mul_f32_e32 v33, 0x37800000, v32
	v_cndmask_b32_e32 v32, v32, v33, vcc
	v_cmp_class_f32_e32 vcc, v31, v131
	s_nop 1
	v_cndmask_b32_e32 v151, v32, v31, vcc
	v_div_scale_f32 v32, s[4:5], v151, v151, 1.0
	v_rcp_f32_e32 v34, v32
	v_add_f32_e32 v31, v16, v17
	v_add_f32_e32 v31, v41, v31
	v_add_f32_e32 v39, v37, v31
	v_fma_f32 v31, -v32, v34, 1.0
	v_fmac_f32_e32 v34, v31, v34
	v_addc_co_u32_e64 v31, vcc, -1, v139, s[2:3]
	global_load_dwordx4 v[58:61], v[30:31], off nt
	v_div_scale_f32 v30, s[4:5], 1.0, v151, 1.0
	v_mul_f32_e32 v35, v30, v34
	v_fma_f32 v31, -v32, v35, v30
	v_fmac_f32_e32 v35, v31, v34
	v_addc_co_u32_e64 v63, vcc, -1, v139, s[28:29]
	v_fma_f32 v37, -v32, v35, v30
	global_load_dwordx4 v[30:33], v[62:63], off nt
	v_add_co_u32_e32 v142, vcc, 0xfffffc00, v138
	s_mov_b64 s[2:3], vcc
	v_addc_co_u32_e64 v55, vcc, -1, v139, s[24:25]
	v_addc_co_u32_e64 v57, vcc, -1, v139, s[26:27]
	global_load_dwordx4 v[110:113], v[54:55], off nt
	global_load_dwordx4 v[86:89], v[56:57], off nt
	s_mov_b64 vcc, s[4:5]
	s_nop 0
	v_div_fmas_f32 v152, v37, v34, v35
	s_waitcnt vmcnt(0)
	v_add_f32_e32 v34, v46, v47
	v_add_f32_e32 v35, v48, v49
	v_addc_co_u32_e64 v37, vcc, -1, v139, s[18:19]
	global_load_dwordx4 v[62:65], v[36:37], off nt
	v_add_f32_e32 v41, v34, v35
	v_addc_co_u32_e64 v53, vcc, -1, v139, s[22:23]
	v_add_f32_e32 v43, v39, v41
	v_addc_co_u32_e64 v39, vcc, -1, v139, s[12:13]
	global_load_dwordx4 v[66:69], v[38:39], off nt
	global_load_dwordx4 v[34:37], v[52:53], off nt
	v_addc_co_u32_e64 v41, vcc, -1, v139, s[16:17]
	global_load_dwordx4 v[114:117], v[40:41], off nt
	v_addc_co_u32_e64 v51, vcc, -1, v139, s[20:21]
	global_load_dwordx4 v[90:93], v[50:51], off nt
	v_addc_co_u32_e64 v45, vcc, -1, v139, s[14:15]
	v_addc_co_u32_e64 v77, vcc, -1, v139, s[42:43]
	global_load_dwordx4 v[94:97], v[76:77], off nt
	v_addc_co_u32_e64 v75, vcc, -1, v139, s[36:37]
	v_addc_co_u32_e64 v81, vcc, -1, v139, s[34:35]
	v_addc_co_u32_e64 v83, vcc, -1, v139, s[38:39]
	s_waitcnt lgkmcnt(0)
	v_add_f32_e32 v40, v26, v27
	v_add_f32_e32 v41, v28, v29
	v_add_f32_e32 v50, v40, v41
	global_load_dwordx4 v[38:41], v[44:45], off nt
	v_add_f32_e32 v144, v43, v50
	v_addc_co_u32_e64 v43, vcc, -1, v139, s[10:11]
	global_load_dwordx4 v[118:121], v[42:43], off nt
	v_addc_co_u32_e64 v79, vcc, -1, v139, s[30:31]
	global_load_dwordx4 v[122:125], v[80:81], off nt
	global_load_dwordx4 v[98:101], v[82:83], off nt
	v_add_f32_e32 v42, v106, v107
	global_load_dwordx4 v[78:81], v[78:79], off nt
	v_add_f32_e32 v43, v108, v109
	global_load_dwordx4 v[74:77], v[74:75], off nt
	v_addc_co_u32_e64 v85, vcc, -1, v139, s[40:41]
	v_add_f32_e32 v50, v42, v43
	global_load_dwordx4 v[42:45], v[84:85], off nt
	v_add_f32_e32 v51, v70, v71
	v_add_f32_e32 v52, v72, v73
	v_addc_co_u32_e64 v103, vcc, -1, v139, s[48:49]
	v_add_f32_e32 v54, v51, v52
	v_add_f32_e32 v55, 0, v50
	global_load_dwordx4 v[50:53], v[102:103], off nt
	v_addc_co_u32_e64 v105, vcc, -1, v139, s[44:45]
	global_load_dwordx4 v[126:129], v[104:105], off nt
	v_addc_co_u32_e64 v141, vcc, -1, v139, s[46:47]
	v_addc_co_u32_e64 v143, vcc, -1, v139, s[2:3]
	global_load_dwordx4 v[82:85], v[142:143], off nt
	global_load_dwordx4 v[102:105], v[140:141], off nt
	v_add_f32_e32 v54, v55, v54
	v_add_f32_e32 v55, v58, v59
	v_add_f32_e32 v56, v60, v61
	v_add_f32_e32 v55, v55, v56
	v_add_f32_e32 v54, v54, v55
	v_add_f32_e32 v55, v30, v31
	v_add_f32_e32 v56, v32, v33
	v_add_f32_e32 v55, v55, v56
	v_add_f32_e32 v140, v54, v55
	s_add_u32 s5, s54, s60
	v_add_f32_e32 v54, v110, v111
	v_add_f32_e32 v55, v112, v113
	v_add_f32_e32 v141, v54, v55
	global_load_dwordx4 v[54:57], v[138:139], off nt
	v_add_f32_e32 v142, v86, v87
	v_add_f32_e32 v143, v88, v89
	v_add_f32_e32 v142, v142, v143
	v_add_f32_e32 v141, 0, v141
	v_add_f32_e32 v141, v141, v142
	s_waitcnt vmcnt(0)
	v_add_f32_e32 v142, v62, v63
	v_add_f32_e32 v143, v64, v65
	v_add_f32_e32 v142, v142, v143
	v_add_f32_e32 v141, v141, v142
	s_addc_u32 s4, s55, s61
	v_add_f32_e32 v142, v34, v35
	v_add_f32_e32 v143, v36, v37
	v_add_f32_e32 v142, v142, v143
	v_add_f32_e32 v141, v141, v142
	v_add_f32_e32 v142, v114, v115
	v_add_f32_e32 v143, v116, v117
	v_add_f32_e32 v142, v142, v143
	v_add_f32_e32 v143, v90, v91
	v_add_f32_e32 v145, v92, v93
	v_add_f32_e32 v143, v143, v145
	v_add_f32_e32 v142, 0, v142
	v_add_f32_e32 v142, v142, v143
	v_add_f32_e32 v143, v66, v67
	v_add_f32_e32 v145, v68, v69
	v_add_f32_e32 v143, v143, v145
	v_add_f32_e32 v142, v142, v143
	v_add_f32_e32 v146, v96, v97
	s_waitcnt lgkmcnt(0)
	v_add_f32_e32 v143, v38, v39
	v_add_f32_e32 v145, v40, v41
	v_add_f32_e32 v143, v143, v145
	v_add_f32_e32 v142, v142, v143
	v_add_f32_e32 v143, v118, v119
	v_add_f32_e32 v145, v120, v121
	v_add_f32_e32 v143, v143, v145
	v_add_f32_e32 v145, v94, v95
	v_add_f32_e32 v145, v145, v146
	v_add_f32_e32 v143, 0, v143
	v_add_f32_e32 v143, v143, v145
	v_add_f32_e32 v147, v100, v101
	v_add_f32_e32 v145, v74, v75
	v_add_f32_e32 v146, v76, v77
	v_add_f32_e32 v145, v145, v146
	v_add_f32_e32 v143, v143, v145
	v_add_f32_e32 v145, v42, v43
	v_add_f32_e32 v146, v44, v45
	v_add_f32_e32 v145, v145, v146
	v_add_f32_e32 v143, v143, v145
	v_add_f32_e32 v145, v122, v123
	v_add_f32_e32 v146, v124, v125
	v_add_f32_e32 v145, v145, v146
	v_add_f32_e32 v146, v98, v99
	v_add_f32_e32 v146, v146, v147
	v_add_f32_e32 v145, 0, v145
	v_add_f32_e32 v145, v145, v146
	v_add_f32_e32 v146, v78, v79
	v_add_f32_e32 v147, v80, v81
	v_add_f32_e32 v146, v146, v147
	ds_swizzle_b32 v147, v144 offset:swizzle(SWAP,1)
	v_add_f32_e32 v145, v145, v146
	v_add_f32_e32 v146, v50, v51
	v_add_f32_e32 v148, v52, v53
	v_add_f32_e32 v146, v146, v148
	s_waitcnt lgkmcnt(0)
	v_add_f32_e32 v144, v144, v147
	ds_swizzle_b32 v147, v144 offset:swizzle(SWAP,2)
	v_add_f32_e32 v145, v145, v146
	v_add_f32_e32 v146, v126, v127
	v_add_f32_e32 v148, v128, v129
	v_add_f32_e32 v146, v146, v148
	s_waitcnt lgkmcnt(0)
	v_add_f32_e32 v144, v144, v147
	ds_swizzle_b32 v147, v144 offset:swizzle(SWAP,4)
	v_add_f32_e32 v148, v102, v103
	v_add_f32_e32 v149, v104, v105
	v_add_f32_e32 v148, v148, v149
	v_add_f32_e32 v146, 0, v146
	s_waitcnt lgkmcnt(0)
	v_add_f32_e32 v144, v144, v147
	ds_swizzle_b32 v147, v144 offset:swizzle(SWAP,8)
	v_add_f32_e32 v146, v146, v148
	v_add_f32_e32 v148, v82, v83
	v_add_f32_e32 v149, v84, v85
	v_add_f32_e32 v148, v148, v149
	s_waitcnt lgkmcnt(0)
	v_add_f32_e32 v144, v144, v147
	ds_swizzle_b32 v147, v144 offset:swizzle(SWAP,16)
	ds_swizzle_b32 v149, v140 offset:swizzle(SWAP,1)
	v_add_f32_e32 v146, v146, v148
	v_add_f32_e32 v148, v54, v55
	v_add_f32_e32 v153, v56, v57
	v_add_f32_e32 v148, v148, v153
	s_waitcnt lgkmcnt(1)
	v_add_f32_e32 v144, v144, v147
	s_waitcnt lgkmcnt(0)
	v_add_f32_e32 v140, v140, v149
	ds_swizzle_b32 v149, v141 offset:swizzle(SWAP,1)
	v_add_f32_e32 v146, v146, v148
	v_mov_b32_e32 v148, v144
	s_nop 1
	v_permlane32_swap_b32_e32 v144, v148
	ds_swizzle_b32 v147, v140 offset:swizzle(SWAP,2)
	v_add_f32_e32 v159, v144, v148
	ds_swizzle_b32 v144, v142 offset:swizzle(SWAP,1)
	s_waitcnt lgkmcnt(2)
	v_add_f32_e32 v141, v141, v149
	ds_swizzle_b32 v149, v141 offset:swizzle(SWAP,2)
	s_waitcnt lgkmcnt(2)
	v_add_f32_e32 v140, v140, v147
	ds_swizzle_b32 v147, v140 offset:swizzle(SWAP,4)
	s_waitcnt lgkmcnt(2)
	v_add_f32_e32 v142, v142, v144
	ds_swizzle_b32 v144, v142 offset:swizzle(SWAP,2)
	s_waitcnt lgkmcnt(2)
	v_add_f32_e32 v141, v141, v149
	ds_swizzle_b32 v148, v141 offset:swizzle(SWAP,4)
	s_waitcnt lgkmcnt(2)
	v_add_f32_e32 v140, v140, v147
	ds_swizzle_b32 v147, v140 offset:swizzle(SWAP,8)
	s_waitcnt lgkmcnt(2)
	v_add_f32_e32 v142, v142, v144
	ds_swizzle_b32 v144, v142 offset:swizzle(SWAP,4)
	s_waitcnt lgkmcnt(2)
	v_add_f32_e32 v141, v141, v148
	ds_swizzle_b32 v148, v141 offset:swizzle(SWAP,8)
	s_waitcnt lgkmcnt(2)
	v_add_f32_e32 v140, v140, v147
	ds_swizzle_b32 v147, v140 offset:swizzle(SWAP,16)
	s_waitcnt lgkmcnt(2)
	v_add_f32_e32 v142, v142, v144
	ds_swizzle_b32 v144, v142 offset:swizzle(SWAP,8)
	s_waitcnt lgkmcnt(2)
	v_add_f32_e32 v141, v141, v148
	ds_swizzle_b32 v148, v141 offset:swizzle(SWAP,16)
	s_waitcnt lgkmcnt(2)
	v_add_f32_e32 v140, v140, v147
	v_mov_b32_e32 v147, v140
	s_waitcnt lgkmcnt(1)
	v_add_f32_e32 v142, v142, v144
	ds_swizzle_b32 v144, v142 offset:swizzle(SWAP,16)
	v_permlane32_swap_b32_e32 v140, v147
	v_add_f32_e32 v158, v140, v147
	s_waitcnt lgkmcnt(1)
	v_add_f32_e32 v140, v141, v148
	ds_swizzle_b32 v147, v143 offset:swizzle(SWAP,1)
	v_mov_b32_e32 v141, v140
	s_nop 1
	v_permlane32_swap_b32_e32 v140, v141
	v_add_f32_e32 v157, v140, v141
	s_waitcnt lgkmcnt(1)
	v_add_f32_e32 v140, v142, v144
	ds_swizzle_b32 v144, v145 offset:swizzle(SWAP,1)
	s_waitcnt lgkmcnt(1)
	v_add_f32_e32 v141, v143, v147
	ds_swizzle_b32 v142, v141 offset:swizzle(SWAP,2)
	v_mov_b32_e32 v143, v140
	s_nop 1
	v_permlane32_swap_b32_e32 v140, v143
	s_waitcnt lgkmcnt(1)
	v_add_f32_e32 v144, v145, v144
	v_add_f32_e32 v156, v140, v143
	ds_swizzle_b32 v140, v146 offset:swizzle(SWAP,1)
	ds_swizzle_b32 v145, v144 offset:swizzle(SWAP,2)
	s_waitcnt lgkmcnt(2)
	v_add_f32_e32 v141, v141, v142
	ds_swizzle_b32 v142, v141 offset:swizzle(SWAP,4)
	v_fmamk_f32 v23, v159, 0xba800000, v23
	s_waitcnt lgkmcnt(2)
	v_add_f32_e32 v140, v146, v140
	s_waitcnt lgkmcnt(1)
	v_add_f32_e32 v143, v144, v145
	ds_swizzle_b32 v145, v140 offset:swizzle(SWAP,2)
	s_waitcnt lgkmcnt(1)
	v_add_f32_e32 v141, v141, v142
	ds_swizzle_b32 v142, v141 offset:swizzle(SWAP,8)
	ds_swizzle_b32 v144, v143 offset:swizzle(SWAP,4)
	v_fmamk_f32 v15, v159, 0xba800000, v15
	s_waitcnt lgkmcnt(2)
	v_add_f32_e32 v140, v140, v145
	ds_swizzle_b32 v145, v140 offset:swizzle(SWAP,4)
	s_waitcnt lgkmcnt(2)
	v_add_f32_e32 v141, v141, v142
	s_waitcnt lgkmcnt(1)
	v_add_f32_e32 v143, v143, v144
	ds_swizzle_b32 v142, v141 offset:swizzle(SWAP,16)
	ds_swizzle_b32 v144, v143 offset:swizzle(SWAP,8)
	s_waitcnt lgkmcnt(2)
	v_add_f32_e32 v140, v140, v145
	ds_swizzle_b32 v145, v140 offset:swizzle(SWAP,8)
	v_fmac_f32_e32 v22, 0xba800000, v159
	s_waitcnt lgkmcnt(2)
	v_add_f32_e32 v141, v141, v142
	s_waitcnt lgkmcnt(1)
	v_add_f32_e32 v143, v143, v144
	v_mov_b32_e32 v142, v141
	ds_swizzle_b32 v144, v143 offset:swizzle(SWAP,16)
	s_nop 0
	v_permlane32_swap_b32_e32 v141, v142
	s_waitcnt lgkmcnt(1)
	v_add_f32_e32 v140, v140, v145
	v_add_f32_e32 v155, v141, v142
	ds_swizzle_b32 v142, v140 offset:swizzle(SWAP,16)
	s_waitcnt lgkmcnt(1)
	v_add_f32_e32 v141, v143, v144
	v_mov_b32_e32 v143, v141
	s_nop 1
	v_permlane32_swap_b32_e32 v141, v143
	s_waitcnt lgkmcnt(0)
	v_add_f32_e32 v140, v140, v142
	v_add_f32_e32 v154, v141, v143
	v_mov_b32_e32 v141, v140
	s_nop 1
	v_permlane32_swap_b32_e32 v140, v141
	v_add_f32_e32 v153, v140, v141
	v_fmamk_f32 v143, v159, 0xba800000, v25
	v_fmamk_f32 v141, v159, 0xba800000, v17
	v_fmamk_f32 v142, v159, 0xba800000, v24
	v_mul_f32_e32 v24, v23, v23
	v_mul_f32_e32 v25, v143, v143
	v_fmamk_f32 v140, v159, 0xba800000, v16
	v_fmac_f32_e32 v14, 0xba800000, v159
	v_mul_f32_e32 v16, v15, v15
	v_mul_f32_e32 v17, v141, v141
	v_fmac_f32_e32 v24, v22, v22
	v_fmac_f32_e32 v25, v142, v142
	v_fmac_f32_e32 v16, v14, v14
	v_fmac_f32_e32 v17, v140, v140
	v_add_f32_e32 v24, v24, v25
	v_add_f32_e32 v16, v16, v17
	v_fmamk_f32 v49, v159, 0xba800000, v49
	v_fmamk_f32 v47, v159, 0xba800000, v47
	v_add_f32_e32 v16, v24, v16
	v_fmamk_f32 v48, v159, 0xba800000, v48
	v_fmac_f32_e32 v46, 0xba800000, v159
	v_mul_f32_e32 v17, v47, v47
	v_mul_f32_e32 v24, v49, v49
	v_fmac_f32_e32 v17, v46, v46
	v_fmac_f32_e32 v24, v48, v48
	v_add_f32_e32 v17, v17, v24
	v_add_f32_e32 v24, v17, v16
	v_fmamk_f32 v17, v159, 0xba800000, v29
	v_fmamk_f32 v27, v159, 0xba800000, v27
	v_fmamk_f32 v16, v159, 0xba800000, v28
	v_fmac_f32_e32 v26, 0xba800000, v159
	v_mul_f32_e32 v25, v27, v27
	v_mul_f32_e32 v28, v17, v17
	v_fmac_f32_e32 v25, v26, v26
	v_fmac_f32_e32 v28, v16, v16
	v_add_f32_e32 v25, v25, v28
	v_fmamk_f32 v109, v158, 0xba800000, v109
	v_fmamk_f32 v107, v158, 0xba800000, v107
	v_add_f32_e32 v160, v25, v24
	v_fmamk_f32 v108, v158, 0xba800000, v108
	v_fmac_f32_e32 v106, 0xba800000, v158
	v_mul_f32_e32 v24, v107, v107
	v_mul_f32_e32 v25, v109, v109
	v_fmac_f32_e32 v24, v106, v106
	v_fmac_f32_e32 v25, v108, v108
	v_fmamk_f32 v73, v158, 0xba800000, v73
	v_fmamk_f32 v71, v158, 0xba800000, v71
	v_add_f32_e32 v24, v24, v25
	v_fmamk_f32 v72, v158, 0xba800000, v72
	v_fmac_f32_e32 v70, 0xba800000, v158
	v_mul_f32_e32 v25, v71, v71
	v_mul_f32_e32 v28, v73, v73
	v_fmac_f32_e32 v25, v70, v70
	v_fmac_f32_e32 v28, v72, v72
	v_add_f32_e32 v25, v25, v28
	v_fmamk_f32 v61, v158, 0xba800000, v61
	v_fmamk_f32 v59, v158, 0xba800000, v59
	v_add_f32_e32 v24, v24, v25
	v_fmamk_f32 v60, v158, 0xba800000, v60
	v_fmac_f32_e32 v58, 0xba800000, v158
	v_mul_f32_e32 v25, v59, v59
	v_mul_f32_e32 v28, v61, v61
	v_fmac_f32_e32 v25, v58, v58
	v_fmac_f32_e32 v28, v60, v60
	v_add_f32_e32 v25, v25, v28
	v_add_f32_e32 v28, v25, v24
	v_fmamk_f32 v25, v158, 0xba800000, v33
	v_fmamk_f32 v31, v158, 0xba800000, v31
	v_fmamk_f32 v24, v158, 0xba800000, v32
	v_fmac_f32_e32 v30, 0xba800000, v158
	v_mul_f32_e32 v29, v31, v31
	v_mul_f32_e32 v32, v25, v25
	v_fmac_f32_e32 v29, v30, v30
	v_fmac_f32_e32 v32, v24, v24
	v_add_f32_e32 v29, v29, v32
	v_fmamk_f32 v113, v157, 0xba800000, v113
	v_fmamk_f32 v111, v157, 0xba800000, v111
	v_add_f32_e32 v161, v29, v28
	v_fmamk_f32 v112, v157, 0xba800000, v112
	v_fmac_f32_e32 v110, 0xba800000, v157
	v_mul_f32_e32 v28, v111, v111
	v_mul_f32_e32 v29, v113, v113
	v_fmac_f32_e32 v28, v110, v110
	v_fmac_f32_e32 v29, v112, v112
	v_fmamk_f32 v89, v157, 0xba800000, v89
	v_fmamk_f32 v87, v157, 0xba800000, v87
	v_add_f32_e32 v28, v28, v29
	v_fmamk_f32 v88, v157, 0xba800000, v88
	v_fmac_f32_e32 v86, 0xba800000, v157
	v_mul_f32_e32 v29, v87, v87
	v_mul_f32_e32 v32, v89, v89
	v_fmac_f32_e32 v29, v86, v86
	v_fmac_f32_e32 v32, v88, v88
	v_add_f32_e32 v29, v29, v32
	v_fmamk_f32 v65, v157, 0xba800000, v65
	v_fmamk_f32 v63, v157, 0xba800000, v63
	v_add_f32_e32 v28, v28, v29
	v_fmamk_f32 v64, v157, 0xba800000, v64
	v_fmac_f32_e32 v62, 0xba800000, v157
	v_mul_f32_e32 v29, v63, v63
	v_mul_f32_e32 v32, v65, v65
	v_fmac_f32_e32 v29, v62, v62
	v_fmac_f32_e32 v32, v64, v64
	v_add_f32_e32 v29, v29, v32
	v_add_f32_e32 v32, v29, v28
	v_fmamk_f32 v29, v157, 0xba800000, v37
	v_fmamk_f32 v35, v157, 0xba800000, v35
	v_fmamk_f32 v28, v157, 0xba800000, v36
	v_fmac_f32_e32 v34, 0xba800000, v157
	v_mul_f32_e32 v33, v35, v35
	v_mul_f32_e32 v36, v29, v29
	v_fmac_f32_e32 v33, v34, v34
	v_fmac_f32_e32 v36, v28, v28
	v_add_f32_e32 v33, v33, v36
	v_fmamk_f32 v117, v156, 0xba800000, v117
	v_fmamk_f32 v115, v156, 0xba800000, v115
	v_add_f32_e32 v162, v33, v32
	v_fmamk_f32 v116, v156, 0xba800000, v116
	v_fmac_f32_e32 v114, 0xba800000, v156
	v_mul_f32_e32 v32, v115, v115
	v_mul_f32_e32 v33, v117, v117
	v_fmac_f32_e32 v32, v114, v114
	v_fmac_f32_e32 v33, v116, v116
	v_fmamk_f32 v93, v156, 0xba800000, v93
	v_fmamk_f32 v91, v156, 0xba800000, v91
	v_add_f32_e32 v32, v32, v33
	v_fmamk_f32 v92, v156, 0xba800000, v92
	v_fmac_f32_e32 v90, 0xba800000, v156
	v_mul_f32_e32 v33, v91, v91
	v_mul_f32_e32 v36, v93, v93
	v_fmac_f32_e32 v33, v90, v90
	v_fmac_f32_e32 v36, v92, v92
	v_add_f32_e32 v33, v33, v36
	v_fmamk_f32 v69, v156, 0xba800000, v69
	v_fmamk_f32 v67, v156, 0xba800000, v67
	v_add_f32_e32 v32, v32, v33
	v_fmamk_f32 v68, v156, 0xba800000, v68
	v_fmac_f32_e32 v66, 0xba800000, v156
	v_mul_f32_e32 v33, v67, v67
	v_mul_f32_e32 v36, v69, v69
	v_fmac_f32_e32 v33, v66, v66
	v_fmac_f32_e32 v36, v68, v68
	v_add_f32_e32 v33, v33, v36
	v_add_f32_e32 v36, v33, v32
	v_fmamk_f32 v33, v156, 0xba800000, v41
	v_fmamk_f32 v39, v156, 0xba800000, v39
	v_fmamk_f32 v32, v156, 0xba800000, v40
	v_fmac_f32_e32 v38, 0xba800000, v156
	v_mul_f32_e32 v37, v39, v39
	v_mul_f32_e32 v40, v33, v33
	v_fmac_f32_e32 v37, v38, v38
	v_fmac_f32_e32 v40, v32, v32
	v_add_f32_e32 v37, v37, v40
	v_fmamk_f32 v145, v155, 0xba800000, v121
	v_fmamk_f32 v119, v155, 0xba800000, v119
	v_add_f32_e32 v163, v37, v36
	v_fmamk_f32 v144, v155, 0xba800000, v120
	v_fmac_f32_e32 v118, 0xba800000, v155
	v_mul_f32_e32 v36, v119, v119
	v_mul_f32_e32 v37, v145, v145
	v_fmac_f32_e32 v36, v118, v118
	v_fmac_f32_e32 v37, v144, v144
	v_fmamk_f32 v97, v155, 0xba800000, v97
	v_fmamk_f32 v95, v155, 0xba800000, v95
	v_add_f32_e32 v36, v36, v37
	v_fmamk_f32 v96, v155, 0xba800000, v96
	v_fmac_f32_e32 v94, 0xba800000, v155
	v_mul_f32_e32 v37, v95, v95
	v_mul_f32_e32 v40, v97, v97
	v_fmac_f32_e32 v37, v94, v94
	v_fmac_f32_e32 v40, v96, v96
	v_add_f32_e32 v37, v37, v40
	v_fmamk_f32 v77, v155, 0xba800000, v77
	v_fmamk_f32 v75, v155, 0xba800000, v75
	v_add_f32_e32 v36, v36, v37
	v_fmamk_f32 v76, v155, 0xba800000, v76
	v_fmac_f32_e32 v74, 0xba800000, v155
	v_mul_f32_e32 v37, v75, v75
	v_mul_f32_e32 v40, v77, v77
	v_fmac_f32_e32 v37, v74, v74
	v_fmac_f32_e32 v40, v76, v76
	v_add_f32_e32 v37, v37, v40
	v_add_f32_e32 v40, v37, v36
	v_fmamk_f32 v37, v155, 0xba800000, v45
	v_fmamk_f32 v43, v155, 0xba800000, v43
	v_fmamk_f32 v36, v155, 0xba800000, v44
	v_fmac_f32_e32 v42, 0xba800000, v155
	v_mul_f32_e32 v41, v43, v43
	v_mul_f32_e32 v44, v37, v37
	v_fmac_f32_e32 v41, v42, v42
	v_fmac_f32_e32 v44, v36, v36
	v_add_f32_e32 v41, v41, v44
	v_fmamk_f32 v147, v154, 0xba800000, v125
	v_fmamk_f32 v123, v154, 0xba800000, v123
	v_add_f32_e32 v121, v41, v40
	v_fmamk_f32 v146, v154, 0xba800000, v124
	v_fmac_f32_e32 v122, 0xba800000, v154
	v_mul_f32_e32 v40, v123, v123
	v_mul_f32_e32 v41, v147, v147
	v_fmac_f32_e32 v40, v122, v122
	v_fmac_f32_e32 v41, v146, v146
	v_fmamk_f32 v101, v154, 0xba800000, v101
	v_fmamk_f32 v99, v154, 0xba800000, v99
	v_add_f32_e32 v40, v40, v41
	v_fmamk_f32 v100, v154, 0xba800000, v100
	v_fmac_f32_e32 v98, 0xba800000, v154
	v_mul_f32_e32 v41, v99, v99
	v_mul_f32_e32 v44, v101, v101
	v_fmac_f32_e32 v41, v98, v98
	v_fmac_f32_e32 v44, v100, v100
	v_add_f32_e32 v41, v41, v44
	v_fmamk_f32 v81, v154, 0xba800000, v81
	v_fmamk_f32 v79, v154, 0xba800000, v79
	v_add_f32_e32 v40, v40, v41
	v_fmamk_f32 v80, v154, 0xba800000, v80
	v_fmac_f32_e32 v78, 0xba800000, v154
	v_mul_f32_e32 v41, v79, v79
	v_mul_f32_e32 v44, v81, v81
	v_fmac_f32_e32 v41, v78, v78
	v_fmac_f32_e32 v44, v80, v80
	v_add_f32_e32 v41, v41, v44
	v_add_f32_e32 v44, v41, v40
	v_fmamk_f32 v41, v154, 0xba800000, v53
	v_fmamk_f32 v51, v154, 0xba800000, v51
	v_fmamk_f32 v40, v154, 0xba800000, v52
	v_fmac_f32_e32 v50, 0xba800000, v154
	v_mul_f32_e32 v45, v51, v51
	v_mul_f32_e32 v52, v41, v41
	v_fmac_f32_e32 v45, v50, v50
	v_fmac_f32_e32 v52, v40, v40
	v_add_f32_e32 v45, v45, v52
	v_fmamk_f32 v149, v153, 0xba800000, v129
	v_fmamk_f32 v127, v153, 0xba800000, v127
	v_add_f32_e32 v124, v45, v44
	v_fmamk_f32 v148, v153, 0xba800000, v128
	v_fmac_f32_e32 v126, 0xba800000, v153
	v_mul_f32_e32 v44, v127, v127
	v_mul_f32_e32 v45, v149, v149
	v_fmac_f32_e32 v44, v126, v126
	v_fmac_f32_e32 v45, v148, v148
	v_fmamk_f32 v105, v153, 0xba800000, v105
	v_fmamk_f32 v103, v153, 0xba800000, v103
	v_add_f32_e32 v44, v44, v45
	v_fmamk_f32 v104, v153, 0xba800000, v104
	v_fmac_f32_e32 v102, 0xba800000, v153
	v_mul_f32_e32 v45, v103, v103
	v_mul_f32_e32 v52, v105, v105
	v_fmac_f32_e32 v45, v102, v102
	v_fmac_f32_e32 v52, v104, v104
	v_fmamk_f32 v53, v153, 0xba800000, v85
	ds_swizzle_b32 v85, v160 offset:swizzle(SWAP,1)
	v_add_f32_e32 v45, v45, v52
	v_fmamk_f32 v83, v153, 0xba800000, v83
	v_add_f32_e32 v44, v44, v45
	v_fmamk_f32 v52, v153, 0xba800000, v84
	v_fmac_f32_e32 v82, 0xba800000, v153
	v_mul_f32_e32 v45, v83, v83
	v_mul_f32_e32 v84, v53, v53
	v_fmac_f32_e32 v45, v82, v82
	v_fmac_f32_e32 v84, v52, v52
	v_add_f32_e32 v45, v45, v84
	v_add_f32_e32 v84, v45, v44
	v_fmamk_f32 v44, v153, 0xba800000, v56
	s_waitcnt lgkmcnt(0)
	v_add_f32_e32 v56, v160, v85
	v_fmamk_f32 v45, v153, 0xba800000, v57
	ds_swizzle_b32 v57, v56 offset:swizzle(SWAP,2)
	ds_swizzle_b32 v120, v161 offset:swizzle(SWAP,1)
	v_fmamk_f32 v55, v153, 0xba800000, v55
	v_fmac_f32_e32 v54, 0xba800000, v153
	v_mul_f32_e32 v85, v55, v55
	s_waitcnt lgkmcnt(1)
	v_add_f32_e32 v56, v56, v57
	ds_swizzle_b32 v57, v56 offset:swizzle(SWAP,4)
	s_waitcnt lgkmcnt(1)
	v_add_f32_e32 v120, v161, v120
	ds_swizzle_b32 v128, v120 offset:swizzle(SWAP,2)
	v_mul_f32_e32 v125, v45, v45
	v_fmac_f32_e32 v85, v54, v54
	s_waitcnt lgkmcnt(1)
	v_add_f32_e32 v56, v56, v57
	ds_swizzle_b32 v57, v56 offset:swizzle(SWAP,8)
	v_fmac_f32_e32 v125, v44, v44
	s_waitcnt lgkmcnt(1)
	v_add_f32_e32 v120, v120, v128
	v_add_f32_e32 v85, v85, v125
	ds_swizzle_b32 v125, v120 offset:swizzle(SWAP,4)
	s_waitcnt lgkmcnt(1)
	v_add_f32_e32 v56, v56, v57
	ds_swizzle_b32 v57, v163 offset:swizzle(SWAP,1)
	ds_swizzle_b32 v128, v162 offset:swizzle(SWAP,1)
	v_add_f32_e32 v85, v85, v84
	s_waitcnt lgkmcnt(2)
	v_add_f32_e32 v84, v120, v125
	ds_swizzle_b32 v160, v56 offset:swizzle(SWAP,16)
	s_waitcnt lgkmcnt(2)
	v_add_f32_e32 v57, v163, v57
	ds_swizzle_b32 v129, v57 offset:swizzle(SWAP,2)
	s_waitcnt lgkmcnt(2)
	v_add_f32_e32 v120, v162, v128
	ds_swizzle_b32 v125, v120 offset:swizzle(SWAP,2)
	ds_swizzle_b32 v128, v84 offset:swizzle(SWAP,8)
	s_waitcnt lgkmcnt(2)
	v_add_f32_e32 v57, v57, v129
	ds_swizzle_b32 v129, v57 offset:swizzle(SWAP,4)
	s_waitcnt lgkmcnt(2)
	v_add_f32_e32 v120, v120, v125
	s_waitcnt lgkmcnt(1)
	v_add_f32_e32 v128, v84, v128
	v_add_f32_e32 v84, v56, v160
	ds_swizzle_b32 v125, v120 offset:swizzle(SWAP,4)
	s_waitcnt lgkmcnt(1)
	v_add_f32_e32 v56, v57, v129
	ds_swizzle_b32 v161, v128 offset:swizzle(SWAP,16)
	ds_swizzle_b32 v57, v56 offset:swizzle(SWAP,8)
	ds_swizzle_b32 v129, v121 offset:swizzle(SWAP,1)
	s_waitcnt lgkmcnt(3)
	v_add_f32_e32 v125, v120, v125
	ds_swizzle_b32 v162, v125 offset:swizzle(SWAP,8)
	s_waitcnt lgkmcnt(3)
	v_add_f32_e32 v120, v128, v161
	s_waitcnt lgkmcnt(2)
	v_add_f32_e32 v56, v56, v57
	ds_swizzle_b32 v57, v124 offset:swizzle(SWAP,1)
	ds_swizzle_b32 v161, v85 offset:swizzle(SWAP,1)
	s_waitcnt lgkmcnt(3)
	v_add_f32_e32 v121, v121, v129
	ds_swizzle_b32 v129, v121 offset:swizzle(SWAP,2)
	s_waitcnt lgkmcnt(3)
	v_add_f32_e32 v125, v125, v162
	s_waitcnt lgkmcnt(2)
	v_add_f32_e32 v57, v124, v57
	s_waitcnt lgkmcnt(1)
	v_add_f32_e32 v85, v85, v161
	ds_swizzle_b32 v124, v57 offset:swizzle(SWAP,2)
	ds_swizzle_b32 v161, v85 offset:swizzle(SWAP,2)
	s_waitcnt lgkmcnt(2)
	v_add_f32_e32 v121, v121, v129
	ds_swizzle_b32 v129, v121 offset:swizzle(SWAP,4)
	ds_swizzle_b32 v128, v125 offset:swizzle(SWAP,16)
	s_waitcnt lgkmcnt(3)
	v_add_f32_e32 v57, v57, v124
	s_waitcnt lgkmcnt(2)
	v_add_f32_e32 v85, v85, v161
	ds_swizzle_b32 v124, v57 offset:swizzle(SWAP,4)
	ds_swizzle_b32 v161, v85 offset:swizzle(SWAP,4)
	s_waitcnt lgkmcnt(3)
	v_add_f32_e32 v121, v121, v129
	ds_swizzle_b32 v129, v121 offset:swizzle(SWAP,8)
	ds_swizzle_b32 v160, v56 offset:swizzle(SWAP,16)
	s_waitcnt lgkmcnt(3)
	v_add_f32_e32 v57, v57, v124
	s_waitcnt lgkmcnt(2)
	v_add_f32_e32 v85, v85, v161
	ds_swizzle_b32 v124, v57 offset:swizzle(SWAP,8)
	ds_swizzle_b32 v161, v85 offset:swizzle(SWAP,8)
	s_waitcnt lgkmcnt(3)
	v_add_f32_e32 v121, v121, v129
	ds_swizzle_b32 v129, v121 offset:swizzle(SWAP,16)
	v_mov_b32_e32 v164, v84
	s_waitcnt lgkmcnt(2)
	v_add_f32_e32 v57, v57, v124
	s_waitcnt lgkmcnt(1)
	v_add_f32_e32 v85, v85, v161
	ds_swizzle_b32 v162, v57 offset:swizzle(SWAP,16)
	ds_swizzle_b32 v161, v85 offset:swizzle(SWAP,16)
	v_add_f32_e32 v124, v125, v128
	v_add_f32_e32 v128, v56, v160
	s_waitcnt lgkmcnt(2)
	v_add_f32_e32 v129, v121, v129
	s_waitcnt lgkmcnt(1)
	v_add_f32_e32 v121, v57, v162
	s_waitcnt lgkmcnt(0)
	v_add_f32_e32 v57, v85, v161
	v_mov_b32_e32 v163, v120
	v_mov_b32_e32 v162, v124
	v_mov_b32_e32 v161, v128
	v_mov_b32_e32 v160, v129
	v_mov_b32_e32 v125, v121
	v_mov_b32_e32 v85, v57
	v_permlane32_swap_b32_e32 v84, v164
	v_permlane32_swap_b32_e32 v120, v163
	v_permlane32_swap_b32_e32 v124, v162
	v_permlane32_swap_b32_e32 v128, v161
	v_permlane32_swap_b32_e32 v129, v160
	v_permlane32_swap_b32_e32 v121, v125
	v_permlane32_swap_b32_e32 v57, v85
	v_div_fixup_f32 v56, v152, v151, 1.0
	s_and_saveexec_b64 s[2:3], s[0:1]
	s_cbranch_execz .LBB0_135
	v_mov_b32_e32 v151, s5
	v_add_co_u32_e32 v166, vcc, 0x1fa00000, v151
	v_mov_b32_e32 v151, s4
	v_mul_f32_e32 v150, 0x3a800000, v150
	v_addc_co_u32_e32 v167, vcc, 0, v151, vcc
	v_mov_b32_e32 v151, v56
	global_store_dwordx2 v[166:167], v[150:151], off
